# chunk-prep wave 7: counted vmcnt(2) instead of vmcnt(0) before taking the next-chunk logits (only its 2 write-through QK stores are younger), and removed the conservative vmcnt(1)/(0) before the cumsu
# baseline (speedup 1.0000x reference)
.LBB0_203:
	s_cmp_gt_i32 s48, 3
	s_mov_b64 s[28:29], -1
	s_waitcnt lgkmcnt(0)
	s_barrier
	s_cbranch_scc0 .LBB0_216
	s_andn2_b64 vcc, exec, s[94:95]
	s_cbranch_vccnz .LBB0_206
	s_waitcnt vmcnt(2)

.LBB0_213:
	s_or_b64 exec, exec, s[28:29]
	s_and_b64 vcc, exec, s[94:95]
	v_mov_b32_e32 v101, v88
	v_mov_b32_e32 v102, v89
	v_mov_b32_e32 v103, v91
	v_mov_b32_e32 v104, v90
	s_cbranch_vccz .LBB0_215
	v_add_f32_e32 v3, v98, v100
	v_max_f32_e32 v4, 0, v3
	v_mul_f32_e64 v3, |v3|, s96
	v_exp_f32_e32 v3, v3
	v_and_b32_e32 v6, 64, v232
	v_add_u32_e32 v7, -1, v232
	v_cmp_lt_i32_e32 vcc, v7, v6
	v_add_f32_e32 v3, 1.0, v3
	v_log_f32_e32 v3, v3
	v_cndmask_b32_e32 v7, v7, v232, vcc
	v_lshlrev_b32_e32 v7, 2, v7
	v_readlane_b32 s6, v254, 27
	v_fmac_f32_e32 v4, 0x3f317218, v3
	v_mul_f32_e32 v3, 0x3fb8aa3b, v97
	v_exp_f32_e32 v3, v3
	v_readlane_b32 s7, v254, 28
	v_mul_f32_e32 v2, 0xbfb8aa3b, v99
	v_exp_f32_e32 v2, v2
	v_mul_f32_e64 v5, v4, -v3
	ds_bpermute_b32 v7, v7, v5
	v_add_f32_e32 v2, 1.0, v2
	v_rcp_f32_e32 v102, v2
	v_lshl_or_b32 v2, v232, 2, v229
	s_waitcnt lgkmcnt(0)
	v_fma_f32 v3, v4, -v3, v7
	v_add_u32_e32 v4, -2, v232
	v_cmp_lt_i32_e32 vcc, v4, v6
	v_cndmask_b32_e64 v3, v3, v5, s[6:7]
	v_readlane_b32 s6, v254, 29
	v_cndmask_b32_e32 v4, v4, v232, vcc
	v_lshlrev_b32_e32 v4, 2, v4
	ds_bpermute_b32 v4, v4, v3
	v_readlane_b32 s7, v254, 30
	s_waitcnt lgkmcnt(0)
	v_add_f32_e32 v4, v3, v4
	v_cndmask_b32_e64 v3, v4, v3, s[6:7]
	v_add_u32_e32 v4, -4, v232
	v_cmp_lt_i32_e32 vcc, v4, v6
	v_readlane_b32 s6, v254, 31
	v_readlane_b32 s7, v254, 32
	v_cndmask_b32_e32 v4, v4, v232, vcc
	v_lshlrev_b32_e32 v4, 2, v4
	ds_bpermute_b32 v4, v4, v3
	s_waitcnt lgkmcnt(0)
	v_add_f32_e32 v4, v3, v4
	v_cndmask_b32_e64 v3, v4, v3, s[6:7]
	v_add_u32_e32 v4, -8, v232
	v_cmp_lt_i32_e32 vcc, v4, v6
	v_readlane_b32 s6, v254, 33
	v_readlane_b32 s7, v254, 34
	v_cndmask_b32_e32 v4, v4, v232, vcc
	v_lshlrev_b32_e32 v4, 2, v4
	ds_bpermute_b32 v4, v4, v3
	s_waitcnt lgkmcnt(0)
	v_add_f32_e32 v4, v3, v4
	v_cndmask_b32_e64 v3, v4, v3, s[6:7]
	v_add_u32_e32 v4, -16, v232
	v_cmp_lt_i32_e32 vcc, v4, v6
	v_readlane_b32 s6, v254, 35
	v_readlane_b32 s7, v254, 36
	v_cndmask_b32_e32 v4, v4, v232, vcc
	v_lshlrev_b32_e32 v4, 2, v4
	ds_bpermute_b32 v4, v4, v3
	s_waitcnt lgkmcnt(0)
	v_add_f32_e32 v4, v3, v4
	v_cndmask_b32_e64 v3, v4, v3, s[6:7]
	v_subrev_u32_e32 v4, 32, v232
	v_cmp_lt_i32_e32 vcc, v4, v6
	v_readlane_b32 s6, v254, 37
	v_readlane_b32 s7, v254, 38
	v_cndmask_b32_e32 v4, v4, v232, vcc
	v_lshlrev_b32_e32 v4, 2, v4
	ds_bpermute_b32 v4, v4, v3
	s_waitcnt lgkmcnt(0)
	v_add_f32_e32 v4, v3, v4
	v_cndmask_b32_e64 v101, v4, v3, s[6:7]
	ds_bpermute_b32 v2, v2, v101
	v_mul_f32_e32 v3, 0x3fb8aa3b, v101
	v_exp_f32_e32 v103, v3
	s_waitcnt lgkmcnt(0)
	v_sub_f32_e32 v2, v2, v101
	v_mul_f32_e32 v2, 0x3fb8aa3b, v2
	v_exp_f32_e32 v104, v2
